# LRU chain loop: per-token LDS reads of gate pass and scan pass hoisted ahead (renamed into v224-v251), K=4
# speedup vs baseline: 1.0020x; 1.0020x over previous
; PH void lru_item(const Params& p, int layer, int b, int n, int dpart) {
;     ...
;     const int base = (b >= 0) ? (b * 2048 + c * 128) : MP;
; #pragma unroll
;     for (int i = 0; i < 6; ++i) {
;       const int idx = tid + 256 * i, r = idx / 12, c16 = idx % 12;
;       *(u32x4*)(xls + r * 104 + c16 * 8) = pxl[i];
;     }
;     u16 gcur[16];
; #pragma unroll
;     for (int t = 0; t < 16; ++t) gcur[t] = pgt[t];
;     {
;       const int nb_ = (c + 1 < nchunks) ? (base + 128) : base;
; #pragma unroll
;       for (int i = 0; i < 6; ++i) {
;         const int idx = tid + 256 * i, r = idx / 12, c16 = idx % 12;
;         pxl[i] = *(const u32x4*)(XL + (size_t)(nb_ + r) * 768 + n * 96 + c16 * 8);
;       }
; #pragma unroll
;       for (int t = 0; t < 16; ++t) pgt[t] = PROJ[(size_t)(nb_ + sub * 16 + t) * NPAD + C_GL + chg];
;     }
;     __syncthreads();
.LBB0_453:
	s_mov_b32 s6, s2
	s_addk_i32 s2, 0x80
	s_cmp_lt_u32 s8, 15
	s_cselect_b32 s9, s2, s6
	v_add_u32_e32 v94, s9, v105
	v_mov_b64_e32 v[166:167], s[4:5]
	v_mad_i64_i32 v[138:139], s[6:7], v94, s97, v[166:167]
	v_lshl_add_u64 v[138:139], v[138:139], 0, v[160:161]
	v_add_co_u32_e32 v138, vcc, s10, v138
	s_waitcnt vmcnt(6)
	ds_write_b128 v126, v[48:51]
	s_waitcnt vmcnt(5)
	ds_write_b128 v127, v[52:55]
	s_waitcnt vmcnt(4)
	ds_write_b128 v128, v[56:59]
	s_waitcnt vmcnt(3)
	ds_write_b128 v129, v[60:63]
	s_waitcnt vmcnt(2)
	ds_write_b128 v130, v[64:67]
	s_waitcnt vmcnt(1)
	ds_write_b128 v131, v[68:71]
	v_addc_co_u32_e32 v139, vcc, 0, v139, vcc
	global_load_ushort v136, v[138:139], off
	v_or_b32_e32 v138, 1, v94
	v_mad_i64_i32 v[138:139], s[6:7], v138, s97, v[166:167]
	v_lshl_add_u64 v[138:139], v[138:139], 0, v[160:161]
	v_add_co_u32_e32 v138, vcc, s10, v138
	v_or_b32_e32 v142, 5, v94
	s_nop 0
	v_addc_co_u32_e32 v139, vcc, 0, v139, vcc
	global_load_ushort v138, v[138:139], off
	v_or_b32_e32 v139, 2, v94
	v_mad_i64_i32 v[140:141], s[6:7], v139, s97, v[166:167]
	v_lshl_add_u64 v[140:141], v[140:141], 0, v[160:161]
	v_add_co_u32_e32 v140, vcc, s10, v140
	v_or_b32_e32 v149, 10, v94
	s_nop 0
	v_addc_co_u32_e32 v141, vcc, 0, v141, vcc
	global_load_ushort v139, v[140:141], off
	v_or_b32_e32 v140, 3, v94
	v_mad_i64_i32 v[140:141], s[6:7], v140, s97, v[166:167]
	v_lshl_add_u64 v[140:141], v[140:141], 0, v[160:161]
	v_add_co_u32_e32 v140, vcc, s10, v140
	v_add_u32_e32 v48, s9, v99
	s_nop 0
	v_addc_co_u32_e32 v141, vcc, 0, v141, vcc
	global_load_ushort v140, v[140:141], off
	v_or_b32_e32 v141, 4, v94
	v_mad_i64_i32 v[144:145], s[6:7], v141, s97, v[166:167]
	v_lshl_add_u64 v[144:145], v[144:145], 0, v[160:161]
	v_add_co_u32_e32 v144, vcc, s10, v144
	v_add_u32_e32 v52, s9, v100
	s_nop 0
	v_addc_co_u32_e32 v145, vcc, 0, v145, vcc
	global_load_ushort v141, v[144:145], off
	v_mad_i64_i32 v[144:145], s[6:7], v142, s97, v[166:167]
	v_lshl_add_u64 v[144:145], v[144:145], 0, v[160:161]
	v_add_co_u32_e32 v144, vcc, s10, v144
	v_add_u32_e32 v56, s9, v101
	s_nop 0
	v_addc_co_u32_e32 v145, vcc, 0, v145, vcc
	global_load_ushort v142, v[144:145], off
	v_or_b32_e32 v144, 6, v94
	v_mad_i64_i32 v[144:145], s[6:7], v144, s97, v[166:167]
	v_lshl_add_u64 v[144:145], v[144:145], 0, v[160:161]
	v_add_co_u32_e32 v144, vcc, s10, v144
	v_add_u32_e32 v60, s9, v102
	s_nop 0
	v_addc_co_u32_e32 v145, vcc, 0, v145, vcc
	global_load_ushort v144, v[144:145], off
	v_or_b32_e32 v145, 7, v94
	v_mad_i64_i32 v[146:147], s[6:7], v145, s97, v[166:167]
	v_lshl_add_u64 v[146:147], v[146:147], 0, v[160:161]
	v_add_co_u32_e32 v146, vcc, s10, v146
	v_add_u32_e32 v64, s9, v103
	s_nop 0
	v_addc_co_u32_e32 v147, vcc, 0, v147, vcc
	global_load_ushort v145, v[146:147], off
	v_or_b32_e32 v146, 8, v94
	v_mad_i64_i32 v[146:147], s[6:7], v146, s97, v[166:167]
	v_lshl_add_u64 v[146:147], v[146:147], 0, v[160:161]
	v_add_co_u32_e32 v146, vcc, s10, v146
	v_add_u32_e32 v68, s9, v104
	s_nop 0
	v_addc_co_u32_e32 v147, vcc, 0, v147, vcc
	global_load_ushort v146, v[146:147], off
	v_or_b32_e32 v147, 9, v94
	v_mad_i64_i32 v[150:151], s[6:7], v147, s97, v[166:167]
	v_lshl_add_u64 v[150:151], v[150:151], 0, v[160:161]
	v_add_co_u32_e32 v150, vcc, s10, v150
	v_mad_i64_i32 v[48:49], s[6:7], v48, s27, v[74:75]
	s_nop 0
	v_addc_co_u32_e32 v151, vcc, 0, v151, vcc
	global_load_ushort v147, v[150:151], off
	v_mad_i64_i32 v[150:151], s[6:7], v149, s97, v[166:167]
	v_lshl_add_u64 v[150:151], v[150:151], 0, v[160:161]
	v_add_co_u32_e32 v150, vcc, s10, v150
	v_mad_i64_i32 v[52:53], s[6:7], v52, s27, v[76:77]
	s_nop 0
	v_addc_co_u32_e32 v151, vcc, 0, v151, vcc
	global_load_ushort v149, v[150:151], off
	v_or_b32_e32 v150, 11, v94
	v_mad_i64_i32 v[150:151], s[6:7], v150, s97, v[166:167]
	v_lshl_add_u64 v[150:151], v[150:151], 0, v[160:161]
	v_add_co_u32_e32 v150, vcc, s10, v150
	v_mad_i64_i32 v[56:57], s[6:7], v56, s27, v[78:79]
	s_nop 0
	v_addc_co_u32_e32 v151, vcc, 0, v151, vcc
	global_load_ushort v150, v[150:151], off
	v_or_b32_e32 v151, 12, v94
	v_mad_i64_i32 v[152:153], s[6:7], v151, s97, v[166:167]
	v_lshl_add_u64 v[152:153], v[152:153], 0, v[160:161]
	v_add_co_u32_e32 v152, vcc, s10, v152
	v_mad_i64_i32 v[60:61], s[6:7], v60, s27, v[80:81]
	s_nop 0
	v_addc_co_u32_e32 v153, vcc, 0, v153, vcc
	global_load_ushort v151, v[152:153], off
	v_or_b32_e32 v152, 13, v94
	v_mad_i64_i32 v[152:153], s[6:7], v152, s97, v[166:167]
	v_lshl_add_u64 v[152:153], v[152:153], 0, v[160:161]
	v_add_co_u32_e32 v152, vcc, s10, v152
	v_mad_i64_i32 v[64:65], s[6:7], v64, s27, v[82:83]
	s_nop 0
	v_addc_co_u32_e32 v153, vcc, 0, v153, vcc
	global_load_ushort v152, v[152:153], off
	v_or_b32_e32 v153, 14, v94
	v_mad_i64_i32 v[168:169], s[6:7], v153, s97, v[166:167]
	v_lshl_add_u64 v[168:169], v[168:169], 0, v[160:161]
	v_or_b32_e32 v94, 15, v94
	v_add_co_u32_e32 v168, vcc, s10, v168
	v_mad_i64_i32 v[166:167], s[6:7], v94, s97, v[166:167]
	s_nop 0
	v_addc_co_u32_e32 v169, vcc, 0, v169, vcc
	v_lshl_add_u64 v[166:167], v[166:167], 0, v[160:161]
	v_add_co_u32_e32 v166, vcc, s10, v166
	v_mad_i64_i32 v[68:69], s[6:7], v68, s27, v[84:85]
	s_nop 0
	v_addc_co_u32_e32 v167, vcc, 0, v167, vcc
	global_load_dwordx4 v[48:51], v[48:49], off
	v_add_u32_e32 v94, 0x6804, v108
	global_load_dwordx4 v[52:55], v[52:53], off
	s_cmp_eq_u32 s0, 0
	global_load_dwordx4 v[56:59], v[56:57], off
	s_nop 0
	global_load_dwordx4 v[60:63], v[60:61], off
	s_nop 0
	global_load_dwordx4 v[64:67], v[64:65], off
	s_nop 0
	global_load_dwordx4 v[68:71], v[68:69], off
	s_nop 0
	global_load_ushort v153, v[168:169], off
	global_load_ushort v155, v[166:167], off
	s_waitcnt lgkmcnt(0)
	s_barrier
; DI float bf2f(u16 b) { return __uint_as_float(((unsigned)b) << 16); }
; DI f32x4 mfma16(bf16x8 a, bf16x8 b, f32x4 c) { return __builtin_amdgcn_mfma_f32_16x16x32_bf16(a, b, c, 0, 0, 0); }
; DI float sigmoid_f(float x) { return __builtin_amdgcn_rcpf(1.f + __expf(-x)); }
; PH void lru_item(const Params& p, int layer, int b, int n, int dpart) {
;     ...
;       f32x4 ra[2][2], rx[2][2];
; #pragma unroll
;       for (int dt = 0; dt < 2; ++dt)
; #pragma unroll
;         for (int tt = 0; tt < 2; ++tt) { ra[dt][tt] = (f32x4){0.f, 0.f, 0.f, 0.f}; rx[dt][tt] = (f32x4){0.f, 0.f, 0.f, 0.f}; }
; #pragma unroll
;       for (int ks = 0; ks < 3; ++ks)
; #pragma unroll
;         for (int tt = 0; tt < 2; ++tt) {
;           const bf16x8 xf = ldfrag(xls, 104, (2 * w + tt) * 16, ks * 32, lane);
; #pragma unroll
;           for (int dt = 0; dt < 2; ++dt) {
;             ra[dt][tt] = mfma16(wa[dt][ks], xf, ra[dt][tt]);
;             rx[dt][tt] = mfma16(wx[dt][ks], xf, rx[dt][tt]);
;           }
;         }
; #pragma unroll
;       for (int dt = 0; dt < 2; ++dt)
; #pragma unroll
;         for (int tt = 0; tt < 2; ++tt)
; #pragma unroll
;           for (int r = 0; r < 4; ++r) {
;             const int tok = (2 * w + tt) * 16 + l15, dl = dt * 16 + quad * 4 + r;
;             as_[tok * 33 + dl] = ra[dt][tt][r];
;             bs_[tok * 33 + dl] = rx[dt][tt][r];
;           }
;     }
;     __syncthreads();
;     float P = 1.f, H = 0.f;
; #pragma unroll
;     for (int t = 0; t < 16; ++t) {
;       const int tok = sub * 16 + t;
;       const float rg = sigmoid_f(as_[tok * 33 + sch] + ba);
;       const float ig = sigmoid_f(bs_[tok * 33 + sch] + bx);
;       const float la = cl * rg;
;       const float xv = bf2f(xls[tok * 104 + dpart * 32 + sch]);
;       const float a = __expf(la);
;       const float bb = __builtin_amdgcn_sqrtf(-expm1f(2.f * la)) * ig * xv;
;       as_[tok * 33 + sch] = a;
;       bs_[tok * 33 + sch] = bb;
;       H = a * H + bb; P *= a;
	ds_read_b128 v[166:169], v132
	ds_read_b128 v[220:223], v132 offset:64
	s_waitcnt lgkmcnt(1)
	v_mfma_f32_16x16x32_bf16 v[170:173], v[0:3], v[166:169], 0
	ds_read_b128 v[204:207], v132 offset:3328
	v_mfma_f32_16x16x32_bf16 v[174:177], v[8:11], v[166:169], 0
	v_mfma_f32_16x16x32_bf16 v[178:181], v[20:23], v[166:169], 0
	v_mfma_f32_16x16x32_bf16 v[166:169], v[28:31], v[166:169], 0
	s_waitcnt lgkmcnt(1)
	v_mfma_f32_16x16x32_bf16 v[170:173], v[4:7], v[220:223], v[170:173]
	v_mfma_f32_16x16x32_bf16 v[174:177], v[12:15], v[220:223], v[174:177]
	v_mfma_f32_16x16x32_bf16 v[178:181], v[32:35], v[220:223], v[178:181]
	v_mfma_f32_16x16x32_bf16 v[166:169], v[40:43], v[220:223], v[166:169]
	ds_read_b128 v[220:223], v132 offset:3392
	s_waitcnt lgkmcnt(1)
	v_mfma_f32_16x16x32_bf16 v[208:211], v[0:3], v[204:207], 0
	v_mfma_f32_16x16x32_bf16 v[212:215], v[8:11], v[204:207], 0
	v_mfma_f32_16x16x32_bf16 v[216:219], v[20:23], v[204:207], 0
	v_mfma_f32_16x16x32_bf16 v[204:207], v[28:31], v[204:207], 0
	s_waitcnt lgkmcnt(0)
	v_mfma_f32_16x16x32_bf16 v[208:211], v[4:7], v[220:223], v[208:211]
	v_mfma_f32_16x16x32_bf16 v[212:215], v[12:15], v[220:223], v[212:215]
	v_mfma_f32_16x16x32_bf16 v[216:219], v[32:35], v[220:223], v[216:219]
	v_mfma_f32_16x16x32_bf16 v[204:207], v[40:43], v[220:223], v[204:207]
	ds_read_b128 v[220:223], v132 offset:128
	s_waitcnt lgkmcnt(0)
	v_mfma_f32_16x16x32_bf16 v[170:173], v[16:19], v[220:223], v[170:173]
	v_mfma_f32_16x16x32_bf16 v[174:177], v[24:27], v[220:223], v[174:177]
	v_mfma_f32_16x16x32_bf16 v[178:181], v[36:39], v[220:223], v[178:181]
	v_mfma_f32_16x16x32_bf16 v[166:169], v[44:47], v[220:223], v[166:169]
	ds_read_b128 v[220:223], v132 offset:3456
	s_nop 3
	ds_write2_b32 v94, v171, v172 offset1:1
	v_add_u32_e32 v94, 0xaa04, v108
	s_waitcnt lgkmcnt(1)
	v_mfma_f32_16x16x32_bf16 v[208:211], v[16:19], v[220:223], v[208:211]
	ds_write2_b32 v94, v175, v176 offset1:1
	v_add_u32_e32 v94, 0x6800, v108
	ds_write2_b32 v94, v170, v173 offset1:3
	v_mfma_f32_16x16x32_bf16 v[212:215], v[24:27], v[220:223], v[212:215]
	v_add_u32_e32 v94, 0xa800, v108
	ds_write2_b32 v94, v174, v177 offset0:128 offset1:131
	v_add_u32_e32 v94, 0x6800, v109
	s_nop 0
	ds_write2_b32 v94, v208, v209 offset1:1
	v_add_u32_e32 v94, 0xaa00, v109
	s_nop 1
	ds_write2_b32 v94, v212, v213 offset1:1
	v_add_u32_e32 v94, 0x6808, v109
	ds_write2_b32 v94, v210, v211 offset1:1
	v_add_u32_e32 v94, 0xaa08, v109
	ds_write2_b32 v94, v214, v215 offset1:1
	v_add_u32_e32 v94, 0x6840, v108
	v_mfma_f32_16x16x32_bf16 v[216:219], v[36:39], v[220:223], v[216:219]
	ds_write2_b32 v94, v178, v179 offset1:1
	v_add_u32_e32 v94, 0xaa40, v108
	ds_write2_b32 v94, v166, v167 offset1:1
	v_mfma_f32_16x16x32_bf16 v[204:207], v[44:47], v[220:223], v[204:207]
	v_add_u32_e32 v94, 0x6840, v110
	ds_write2_b32 v94, v180, v181 offset1:1
	v_add_u32_e32 v94, 0xaa40, v110
	ds_write2_b32 v94, v168, v169 offset1:1
	v_add_u32_e32 v94, 0x6840, v109
	ds_write2_b32 v94, v216, v217 offset1:1
	v_add_u32_e32 v94, 0xaa40, v109
	s_nop 0
	ds_write2_b32 v94, v204, v205 offset1:1
	v_add_u32_e32 v94, 0x6840, v111
	ds_write2_b32 v94, v218, v219 offset1:1
	v_add_u32_e32 v94, 0xaa40, v111
	ds_write2_b32 v94, v206, v207 offset1:1
	s_waitcnt lgkmcnt(0)
	s_barrier
	ds_read2st64_b32 v[166:167], v86 offset0:104 offset1:170
	ds_read_u16 v224, v133
	ds_read2st64_b32 v[228:229], v88 offset0:104 offset1:170
	ds_read_u16 v232, v134
	ds_read2st64_b32 v[236:237], v87 offset0:104 offset1:170
	s_nop 0
	s_waitcnt lgkmcnt(4)
	v_add_f32_e32 v94, v73, v166
	v_mul_f32_e32 v94, 0xbfb8aa3b, v94
	v_exp_f32_e32 v94, v94
	v_add_f32_e32 v166, v98, v167
	v_mul_f32_e32 v166, 0xbfb8aa3b, v166
	v_exp_f32_e32 v166, v166
	v_add_f32_e32 v94, 1.0, v94
	v_rcp_f32_e32 v94, v94
	v_add_f32_e32 v166, 1.0, v166
	v_rcp_f32_e32 v166, v166
	v_mul_f32_e32 v167, v106, v94
	s_nop 0
	s_nop 0
	s_waitcnt lgkmcnt(3)
	v_lshlrev_b32_e32 v168, 16, v224
	ds_read_u16 v224, v134 offset:208
	v_mul_f32_e32 v94, 0x3fb8aa3b, v167
	v_add_f32_e32 v167, v167, v167
	v_mul_f32_e32 v169, 0x3fb8aa3b, v167
	v_rndne_f32_e32 v169, v169
	v_fmamk_f32 v170, v169, 0xbf317218, v167
	v_fmac_f32_e32 v170, 0x3102e308, v169
	v_fmamk_f32 v171, v170, 0x395133b1, v185
	v_cmp_eq_f32_e32 vcc, s35, v169
	v_cvt_i32_f32_e32 v169, v169
	v_fmaak_f32 v171, v170, v171, 0x3c0887f9
	v_fmaak_f32 v171, v170, v171, 0x3d2aaa81
	v_fmaak_f32 v171, v170, v171, 0x3e2aaaab
	v_fma_f32 v171, v170, v171, 0.5
	v_ldexp_f32 v169, 1.0, v169
	v_mul_f32_e32 v171, v170, v171
	v_cndmask_b32_e32 v169, v169, v198, vcc
	v_fmac_f32_e32 v170, v170, v171
	v_add_f32_e32 v171, -1.0, v169
	v_fmac_f32_e32 v171, v169, v170
	v_add_f32_e32 v169, v171, v171
	v_cndmask_b32_e32 v169, v171, v169, vcc
	v_cmp_nlt_f32_e32 vcc, s33, v167
	v_exp_f32_e32 v94, v94
	s_nop 0
	v_cndmask_b32_e64 v169, v191, -v169, vcc
	v_cmp_ngt_f32_e32 vcc, s12, v167
	s_nop 1
	v_cndmask_b32_e32 v167, 1.0, v169, vcc
	v_sqrt_f32_e32 v167, v167
	s_nop 0
	v_mul_f32_e32 v166, v166, v167
	v_mul_f32_e32 v166, v166, v168
	s_nop 0
	ds_write2st64_b32 v86, v94, v166 offset0:104 offset1:170
	v_fmac_f32_e32 v166, 0, v94
	s_nop 0
	s_waitcnt lgkmcnt(4)
	v_add_f32_e32 v167, v73, v228
	v_mul_f32_e32 v167, 0xbfb8aa3b, v167
	v_exp_f32_e32 v167, v167
	v_add_f32_e32 v168, v98, v229
	ds_read2st64_b32 v[228:229], v89 offset0:104 offset1:170
	v_mul_f32_e32 v168, 0xbfb8aa3b, v168
	v_exp_f32_e32 v168, v168
	v_add_f32_e32 v167, 1.0, v167
	v_rcp_f32_e32 v167, v167
	v_add_f32_e32 v168, 1.0, v168
	v_rcp_f32_e32 v168, v168
	v_mul_f32_e32 v169, v106, v167
	s_nop 0
	s_nop 0
	s_waitcnt lgkmcnt(4)
; DI float bf2f(u16 b) { return __uint_as_float(((unsigned)b) << 16); }
; DI float sigmoid_f(float x) { return __builtin_amdgcn_rcpf(1.f + __expf(-x)); }
; PH void lru_item(const Params& p, int layer, int b, int n, int dpart) {
;     ...
;     for (int t = 0; t < 16; ++t) {
;       const int tok = sub * 16 + t;
;       const float rg = sigmoid_f(as_[tok * 33 + sch] + ba);
;       const float ig = sigmoid_f(bs_[tok * 33 + sch] + bx);
;       const float la = cl * rg;
;       const float xv = bf2f(xls[tok * 104 + dpart * 32 + sch]);
;       const float a = __expf(la);
;       const float bb = __builtin_amdgcn_sqrtf(-expm1f(2.f * la)) * ig * xv;
;       as_[tok * 33 + sch] = a;
;       bs_[tok * 33 + sch] = bb;
;       H = a * H + bb; P *= a;
	v_lshlrev_b32_e32 v170, 16, v232
	ds_read_u16 v232, v134 offset:416
	v_mul_f32_e32 v167, 0x3fb8aa3b, v169
	v_add_f32_e32 v169, v169, v169
	v_mul_f32_e32 v171, 0x3fb8aa3b, v169
	v_rndne_f32_e32 v171, v171
	v_fmamk_f32 v172, v171, 0xbf317218, v169
	v_fmac_f32_e32 v172, 0x3102e308, v171
	v_fmamk_f32 v173, v172, 0x395133b1, v185
	v_cmp_eq_f32_e32 vcc, s35, v171
	v_cvt_i32_f32_e32 v171, v171
	v_fmaak_f32 v173, v172, v173, 0x3c0887f9
	v_fmaak_f32 v173, v172, v173, 0x3d2aaa81
	v_fmaak_f32 v173, v172, v173, 0x3e2aaaab
	v_fma_f32 v173, v172, v173, 0.5
	v_ldexp_f32 v171, 1.0, v171
	v_mul_f32_e32 v173, v172, v173
	v_cndmask_b32_e32 v171, v171, v198, vcc
	v_fmac_f32_e32 v172, v172, v173
	v_add_f32_e32 v173, -1.0, v171
	v_fmac_f32_e32 v173, v171, v172
	v_add_f32_e32 v171, v173, v173
	v_cndmask_b32_e32 v171, v173, v171, vcc
	v_cmp_nlt_f32_e32 vcc, s33, v169
	v_exp_f32_e32 v167, v167
	s_nop 0
	v_cndmask_b32_e64 v171, v191, -v171, vcc
	v_cmp_ngt_f32_e32 vcc, s12, v169
	s_nop 1
	v_cndmask_b32_e32 v169, 1.0, v171, vcc
	v_sqrt_f32_e32 v169, v169
	s_nop 0
	v_mul_f32_e32 v168, v168, v169
	v_mul_f32_e32 v168, v168, v170
	s_nop 0
	ds_write2st64_b32 v88, v167, v168 offset0:104 offset1:170
	v_fmac_f32_e32 v168, v167, v166
	s_nop 0
	s_waitcnt lgkmcnt(5)
	v_add_f32_e32 v169, v73, v236
	v_mul_f32_e32 v169, 0xbfb8aa3b, v169
	v_exp_f32_e32 v169, v169
	v_add_f32_e32 v170, v98, v237
	ds_read2st64_b32 v[236:237], v112 offset0:104 offset1:170
	v_mul_f32_e32 v170, 0xbfb8aa3b, v170
	v_exp_f32_e32 v170, v170
	v_add_f32_e32 v169, 1.0, v169
	v_rcp_f32_e32 v169, v169
	v_add_f32_e32 v170, 1.0, v170
	v_rcp_f32_e32 v170, v170
	v_mul_f32_e32 v171, v106, v169
	s_nop 0
	s_nop 0
	s_waitcnt lgkmcnt(5)
	v_lshlrev_b32_e32 v172, 16, v224
	ds_read_u16 v224, v134 offset:624
	v_mul_f32_e32 v169, 0x3fb8aa3b, v171
	v_add_f32_e32 v171, v171, v171
	v_mul_f32_e32 v173, 0x3fb8aa3b, v171
	v_rndne_f32_e32 v173, v173
	v_fmamk_f32 v174, v173, 0xbf317218, v171
	v_fmac_f32_e32 v174, 0x3102e308, v173
	v_fmamk_f32 v175, v174, 0x395133b1, v185
	v_cmp_eq_f32_e32 vcc, s35, v173
	v_cvt_i32_f32_e32 v173, v173
	v_fmaak_f32 v175, v174, v175, 0x3c0887f9
	v_fmaak_f32 v175, v174, v175, 0x3d2aaa81
	v_fmaak_f32 v175, v174, v175, 0x3e2aaaab
	v_fma_f32 v175, v174, v175, 0.5
	v_ldexp_f32 v173, 1.0, v173
	v_mul_f32_e32 v175, v174, v175
	v_cndmask_b32_e32 v173, v173, v198, vcc
	v_fmac_f32_e32 v174, v174, v175
	v_add_f32_e32 v175, -1.0, v173
	v_fmac_f32_e32 v175, v173, v174
	v_add_f32_e32 v173, v175, v175
	v_cndmask_b32_e32 v173, v175, v173, vcc
	v_cmp_nlt_f32_e32 vcc, s33, v171
	v_exp_f32_e32 v169, v169
	s_nop 0
	v_cndmask_b32_e64 v173, v191, -v173, vcc
	v_cmp_ngt_f32_e32 vcc, s12, v171
	s_nop 1
	v_cndmask_b32_e32 v171, 1.0, v173, vcc
	v_sqrt_f32_e32 v171, v171
	s_nop 0
	v_mul_f32_e32 v170, v170, v171
	v_mul_f32_e32 v170, v170, v172
	s_nop 0
	ds_write2st64_b32 v87, v169, v170 offset0:104 offset1:170
	v_fmac_f32_e32 v170, v169, v168
	s_nop 0
	s_waitcnt lgkmcnt(5)
	v_add_f32_e32 v171, v73, v228
	v_mul_f32_e32 v171, 0xbfb8aa3b, v171
	v_exp_f32_e32 v171, v171
	v_add_f32_e32 v172, v98, v229
	ds_read2st64_b32 v[228:229], v113 offset0:104 offset1:170
	v_mul_f32_e32 v172, 0xbfb8aa3b, v172
	v_exp_f32_e32 v172, v172
	v_add_f32_e32 v171, 1.0, v171
	v_rcp_f32_e32 v171, v171
	v_add_f32_e32 v172, 1.0, v172
	v_rcp_f32_e32 v172, v172
	v_mul_f32_e32 v173, v106, v171
	s_nop 0
	s_nop 0
	s_waitcnt lgkmcnt(5)
	v_lshlrev_b32_e32 v174, 16, v232
	ds_read_u16 v232, v134 offset:832
	v_mul_f32_e32 v171, 0x3fb8aa3b, v173
	v_add_f32_e32 v173, v173, v173
	v_mul_f32_e32 v175, 0x3fb8aa3b, v173
	v_rndne_f32_e32 v175, v175
	v_fmamk_f32 v176, v175, 0xbf317218, v173
	v_fmac_f32_e32 v176, 0x3102e308, v175
	v_fmamk_f32 v177, v176, 0x395133b1, v185
	v_cmp_eq_f32_e32 vcc, s35, v175
	v_cvt_i32_f32_e32 v175, v175
	v_fmaak_f32 v177, v176, v177, 0x3c0887f9
	v_fmaak_f32 v177, v176, v177, 0x3d2aaa81
	v_fmaak_f32 v177, v176, v177, 0x3e2aaaab
	v_fma_f32 v177, v176, v177, 0.5
	v_ldexp_f32 v175, 1.0, v175
	v_mul_f32_e32 v177, v176, v177
	v_cndmask_b32_e32 v175, v175, v198, vcc
	v_fmac_f32_e32 v176, v176, v177
	v_add_f32_e32 v177, -1.0, v175
	v_fmac_f32_e32 v177, v175, v176
	v_add_f32_e32 v175, v177, v177
	v_cndmask_b32_e32 v175, v177, v175, vcc
	v_cmp_nlt_f32_e32 vcc, s33, v173
	v_exp_f32_e32 v171, v171
	s_nop 0
	v_cndmask_b32_e64 v175, v191, -v175, vcc
	v_cmp_ngt_f32_e32 vcc, s12, v173
	s_nop 1
	v_cndmask_b32_e32 v173, 1.0, v175, vcc
	v_sqrt_f32_e32 v173, v173
	s_nop 0
	v_mul_f32_e32 v172, v172, v173
	v_mul_f32_e32 v172, v172, v174
	s_nop 0
	ds_write2st64_b32 v89, v171, v172 offset0:104 offset1:170
	v_fmac_f32_e32 v172, v171, v170
	s_nop 0
	s_waitcnt lgkmcnt(5)
	v_add_f32_e32 v173, v73, v236
	v_mul_f32_e32 v173, 0xbfb8aa3b, v173
	v_exp_f32_e32 v173, v173
	v_add_f32_e32 v174, v98, v237
	ds_read2st64_b32 v[236:237], v114 offset0:104 offset1:170
	v_mul_f32_e32 v174, 0xbfb8aa3b, v174
	v_exp_f32_e32 v174, v174
	v_add_f32_e32 v173, 1.0, v173
	v_rcp_f32_e32 v173, v173
	v_add_f32_e32 v174, 1.0, v174
	v_rcp_f32_e32 v174, v174
	v_mul_f32_e32 v175, v106, v173
	s_nop 0
	s_nop 0
	s_waitcnt lgkmcnt(5)
; DI float bf2f(u16 b) { return __uint_as_float(((unsigned)b) << 16); }
; DI float sigmoid_f(float x) { return __builtin_amdgcn_rcpf(1.f + __expf(-x)); }
; PH void lru_item(const Params& p, int layer, int b, int n, int dpart) {
;     ...
;     float P = 1.f, H = 0.f;
; #pragma unroll
;     for (int t = 0; t < 16; ++t) {
;       const int tok = sub * 16 + t;
;       const float rg = sigmoid_f(as_[tok * 33 + sch] + ba);
;       const float ig = sigmoid_f(bs_[tok * 33 + sch] + bx);
;       const float la = cl * rg;
;       const float xv = bf2f(xls[tok * 104 + dpart * 32 + sch]);
;       const float a = __expf(la);
;       const float bb = __builtin_amdgcn_sqrtf(-expm1f(2.f * la)) * ig * xv;
;       as_[tok * 33 + sch] = a;
;       bs_[tok * 33 + sch] = bb;
;       H = a * H + bb; P *= a;
;     }
	v_lshlrev_b32_e32 v176, 16, v224
	ds_read_u16 v224, v134 offset:1040
	v_mul_f32_e32 v173, 0x3fb8aa3b, v175
	v_add_f32_e32 v175, v175, v175
	v_mul_f32_e32 v177, 0x3fb8aa3b, v175
	v_rndne_f32_e32 v177, v177
	v_fmamk_f32 v178, v177, 0xbf317218, v175
	v_fmac_f32_e32 v178, 0x3102e308, v177
	v_fmamk_f32 v179, v178, 0x395133b1, v185
	v_cmp_eq_f32_e32 vcc, s35, v177
	v_cvt_i32_f32_e32 v177, v177
	v_fmaak_f32 v179, v178, v179, 0x3c0887f9
	v_fmaak_f32 v179, v178, v179, 0x3d2aaa81
	v_fmaak_f32 v179, v178, v179, 0x3e2aaaab
	v_fma_f32 v179, v178, v179, 0.5
	v_ldexp_f32 v177, 1.0, v177
	v_mul_f32_e32 v179, v178, v179
	v_cndmask_b32_e32 v177, v177, v198, vcc
	v_fmac_f32_e32 v178, v178, v179
	v_add_f32_e32 v179, -1.0, v177
	v_fmac_f32_e32 v179, v177, v178
	v_add_f32_e32 v177, v179, v179
	v_cndmask_b32_e32 v177, v179, v177, vcc
	v_cmp_nlt_f32_e32 vcc, s33, v175
	v_exp_f32_e32 v173, v173
	s_nop 0
	v_cndmask_b32_e64 v177, v191, -v177, vcc
	v_cmp_ngt_f32_e32 vcc, s12, v175
	s_nop 1
	v_cndmask_b32_e32 v175, 1.0, v177, vcc
	v_sqrt_f32_e32 v175, v175
	s_nop 0
	v_mul_f32_e32 v174, v174, v175
	v_mul_f32_e32 v174, v174, v176
	ds_write2st64_b32 v112, v173, v174 offset0:104 offset1:170
	s_nop 0
	v_fmac_f32_e32 v174, v173, v172
	s_nop 0
	s_waitcnt lgkmcnt(5)
	v_add_f32_e32 v175, v73, v228
	v_mul_f32_e32 v175, 0xbfb8aa3b, v175
	v_exp_f32_e32 v175, v175
	v_add_f32_e32 v176, v98, v229
	ds_read2st64_b32 v[228:229], v115 offset0:104 offset1:170
	v_mul_f32_e32 v176, 0xbfb8aa3b, v176
	v_exp_f32_e32 v176, v176
	v_add_f32_e32 v175, 1.0, v175
	v_rcp_f32_e32 v175, v175
	v_add_f32_e32 v176, 1.0, v176
	v_rcp_f32_e32 v176, v176
	v_mul_f32_e32 v177, v106, v175
	s_nop 0
	s_nop 0
	s_waitcnt lgkmcnt(5)
	v_lshlrev_b32_e32 v178, 16, v232
	ds_read_u16 v232, v134 offset:1248
	v_mul_f32_e32 v175, 0x3fb8aa3b, v177
	v_add_f32_e32 v177, v177, v177
	v_mul_f32_e32 v179, 0x3fb8aa3b, v177
	v_rndne_f32_e32 v179, v179
	v_fmamk_f32 v180, v179, 0xbf317218, v177
	v_fmac_f32_e32 v180, 0x3102e308, v179
	v_fmamk_f32 v181, v180, 0x395133b1, v185
	v_cmp_eq_f32_e32 vcc, s35, v179
	v_cvt_i32_f32_e32 v179, v179
	v_fmaak_f32 v181, v180, v181, 0x3c0887f9
	v_fmaak_f32 v181, v180, v181, 0x3d2aaa81
	v_fmaak_f32 v181, v180, v181, 0x3e2aaaab
	v_fma_f32 v181, v180, v181, 0.5
	v_ldexp_f32 v179, 1.0, v179
	v_mul_f32_e32 v181, v180, v181
	v_cndmask_b32_e32 v179, v179, v198, vcc
	v_fmac_f32_e32 v180, v180, v181
	v_add_f32_e32 v181, -1.0, v179
	v_fmac_f32_e32 v181, v179, v180
	v_add_f32_e32 v179, v181, v181
	v_cndmask_b32_e32 v179, v181, v179, vcc
	v_cmp_nlt_f32_e32 vcc, s33, v177
	v_exp_f32_e32 v175, v175
	s_nop 0
	v_cndmask_b32_e64 v179, v191, -v179, vcc
	v_cmp_ngt_f32_e32 vcc, s12, v177
	s_nop 1
	v_cndmask_b32_e32 v177, 1.0, v179, vcc
	v_sqrt_f32_e32 v177, v177
	s_nop 0
	v_mul_f32_e32 v176, v176, v177
	v_mul_f32_e32 v176, v176, v178
	ds_write2st64_b32 v113, v175, v176 offset0:104 offset1:170
	s_nop 0
	v_fmac_f32_e32 v176, v175, v174
	s_nop 0
	s_waitcnt lgkmcnt(5)
	v_add_f32_e32 v177, v73, v236
	v_mul_f32_e32 v177, 0xbfb8aa3b, v177
	v_exp_f32_e32 v177, v177
	v_add_f32_e32 v178, v98, v237
	ds_read2st64_b32 v[236:237], v116 offset0:104 offset1:170
	v_mul_f32_e32 v178, 0xbfb8aa3b, v178
	v_exp_f32_e32 v178, v178
	v_add_f32_e32 v177, 1.0, v177
	v_rcp_f32_e32 v177, v177
	v_add_f32_e32 v178, 1.0, v178
	v_rcp_f32_e32 v178, v178
	v_mul_f32_e32 v179, v106, v177
	s_nop 0
	s_nop 0
	s_waitcnt lgkmcnt(5)
	v_lshlrev_b32_e32 v180, 16, v224
	ds_read_u16 v224, v134 offset:1456
	v_mul_f32_e32 v177, 0x3fb8aa3b, v179
	v_add_f32_e32 v179, v179, v179
	v_mul_f32_e32 v181, 0x3fb8aa3b, v179
	v_rndne_f32_e32 v181, v181
	v_fmamk_f32 v203, v181, 0xbf317218, v179
	v_fmac_f32_e32 v203, 0x3102e308, v181
	v_fmamk_f32 v204, v203, 0x395133b1, v185
	v_cmp_eq_f32_e32 vcc, s35, v181
	v_cvt_i32_f32_e32 v181, v181
	v_fmaak_f32 v204, v203, v204, 0x3c0887f9
	v_fmaak_f32 v204, v203, v204, 0x3d2aaa81
	v_fmaak_f32 v204, v203, v204, 0x3e2aaaab
	v_fma_f32 v204, v203, v204, 0.5
	v_ldexp_f32 v181, 1.0, v181
	v_mul_f32_e32 v204, v203, v204
	v_cndmask_b32_e32 v181, v181, v198, vcc
	v_fmac_f32_e32 v203, v203, v204
	v_add_f32_e32 v204, -1.0, v181
	v_fmac_f32_e32 v204, v181, v203
	v_add_f32_e32 v181, v204, v204
	v_cndmask_b32_e32 v181, v204, v181, vcc
	v_cmp_nlt_f32_e32 vcc, s33, v179
	v_exp_f32_e32 v177, v177
	s_nop 0
	v_cndmask_b32_e64 v181, v191, -v181, vcc
	v_cmp_ngt_f32_e32 vcc, s12, v179
	s_nop 1
	v_cndmask_b32_e32 v179, 1.0, v181, vcc
	v_sqrt_f32_e32 v179, v179
	s_nop 0
	v_mul_f32_e32 v178, v178, v179
	v_mul_f32_e32 v178, v178, v180
	ds_write2st64_b32 v114, v177, v178 offset0:104 offset1:170
	s_nop 0
	v_fmac_f32_e32 v178, v177, v176
	s_nop 0
	s_waitcnt lgkmcnt(5)
	v_add_f32_e32 v179, v73, v228
	v_mul_f32_e32 v179, 0xbfb8aa3b, v179
	v_exp_f32_e32 v179, v179
	v_add_f32_e32 v180, v98, v229
	ds_read2st64_b32 v[228:229], v117 offset0:104 offset1:170
	v_mul_f32_e32 v180, 0xbfb8aa3b, v180
	v_exp_f32_e32 v180, v180
	v_add_f32_e32 v179, 1.0, v179
	v_rcp_f32_e32 v179, v179
	v_add_f32_e32 v180, 1.0, v180
	v_rcp_f32_e32 v180, v180
	v_mul_f32_e32 v181, v106, v179
	s_nop 0
	s_nop 0
	s_waitcnt lgkmcnt(5)
; DI float bf2f(u16 b) { return __uint_as_float(((unsigned)b) << 16); }
; DI float sigmoid_f(float x) { return __builtin_amdgcn_rcpf(1.f + __expf(-x)); }
; PH void lru_item(const Params& p, int layer, int b, int n, int dpart) {
;     ...
;     float P = 1.f, H = 0.f;
; #pragma unroll
;     for (int t = 0; t < 16; ++t) {
;       const int tok = sub * 16 + t;
;       const float rg = sigmoid_f(as_[tok * 33 + sch] + ba);
;       const float ig = sigmoid_f(bs_[tok * 33 + sch] + bx);
;       const float la = cl * rg;
;       const float xv = bf2f(xls[tok * 104 + dpart * 32 + sch]);
;       const float a = __expf(la);
;       const float bb = __builtin_amdgcn_sqrtf(-expm1f(2.f * la)) * ig * xv;
;       as_[tok * 33 + sch] = a;
;       bs_[tok * 33 + sch] = bb;
;       H = a * H + bb; P *= a;
;     }
	v_lshlrev_b32_e32 v203, 16, v232
	ds_read_u16 v232, v134 offset:1664
	v_mul_f32_e32 v179, 0x3fb8aa3b, v181
	v_add_f32_e32 v181, v181, v181
	v_mul_f32_e32 v204, 0x3fb8aa3b, v181
	v_rndne_f32_e32 v204, v204
	v_fmamk_f32 v205, v204, 0xbf317218, v181
	v_fmac_f32_e32 v205, 0x3102e308, v204
	v_fmamk_f32 v206, v205, 0x395133b1, v185
	v_cmp_eq_f32_e32 vcc, s35, v204
	v_cvt_i32_f32_e32 v204, v204
	v_fmaak_f32 v206, v205, v206, 0x3c0887f9
	v_fmaak_f32 v206, v205, v206, 0x3d2aaa81
	v_fmaak_f32 v206, v205, v206, 0x3e2aaaab
	v_fma_f32 v206, v205, v206, 0.5
	v_ldexp_f32 v204, 1.0, v204
	v_mul_f32_e32 v206, v205, v206
	v_cndmask_b32_e32 v204, v204, v198, vcc
	v_fmac_f32_e32 v205, v205, v206
	v_add_f32_e32 v206, -1.0, v204
	v_fmac_f32_e32 v206, v204, v205
	v_add_f32_e32 v204, v206, v206
	v_cndmask_b32_e32 v204, v206, v204, vcc
	v_cmp_nlt_f32_e32 vcc, s33, v181
	v_exp_f32_e32 v179, v179
	s_nop 0
	v_cndmask_b32_e64 v204, v191, -v204, vcc
	v_cmp_ngt_f32_e32 vcc, s12, v181
	s_nop 1
	v_cndmask_b32_e32 v181, 1.0, v204, vcc
	v_sqrt_f32_e32 v181, v181
	s_nop 0
	v_mul_f32_e32 v180, v180, v181
	v_mul_f32_e32 v180, v180, v203
	ds_write2st64_b32 v115, v179, v180 offset0:104 offset1:170
	s_nop 0
	v_fmac_f32_e32 v180, v179, v178
	s_nop 0
	s_waitcnt lgkmcnt(5)
	v_add_f32_e32 v181, v73, v236
	v_mul_f32_e32 v181, 0xbfb8aa3b, v181
	v_exp_f32_e32 v181, v181
	v_add_f32_e32 v203, v98, v237
	ds_read2st64_b32 v[236:237], v118 offset0:104 offset1:170
	v_mul_f32_e32 v203, 0xbfb8aa3b, v203
	v_exp_f32_e32 v203, v203
	v_add_f32_e32 v181, 1.0, v181
	v_rcp_f32_e32 v181, v181
	v_add_f32_e32 v203, 1.0, v203
	v_rcp_f32_e32 v203, v203
	v_mul_f32_e32 v204, v106, v181
	s_nop 0
	s_nop 0
	s_waitcnt lgkmcnt(5)
	v_lshlrev_b32_e32 v205, 16, v224
	ds_read_u16 v224, v134 offset:1872
	v_mul_f32_e32 v181, 0x3fb8aa3b, v204
	v_add_f32_e32 v204, v204, v204
	v_mul_f32_e32 v206, 0x3fb8aa3b, v204
	v_rndne_f32_e32 v206, v206
	v_fmamk_f32 v207, v206, 0xbf317218, v204
	v_fmac_f32_e32 v207, 0x3102e308, v206
	v_fmamk_f32 v208, v207, 0x395133b1, v185
	v_cmp_eq_f32_e32 vcc, s35, v206
	v_cvt_i32_f32_e32 v206, v206
	v_fmaak_f32 v208, v207, v208, 0x3c0887f9
	v_fmaak_f32 v208, v207, v208, 0x3d2aaa81
	v_fmaak_f32 v208, v207, v208, 0x3e2aaaab
	v_fma_f32 v208, v207, v208, 0.5
	v_ldexp_f32 v206, 1.0, v206
	v_mul_f32_e32 v208, v207, v208
	v_cndmask_b32_e32 v206, v206, v198, vcc
	v_fmac_f32_e32 v207, v207, v208
	v_add_f32_e32 v208, -1.0, v206
	v_fmac_f32_e32 v208, v206, v207
	v_add_f32_e32 v206, v208, v208
	v_cndmask_b32_e32 v206, v208, v206, vcc
	v_cmp_nlt_f32_e32 vcc, s33, v204
	v_exp_f32_e32 v181, v181
	s_nop 0
	v_cndmask_b32_e64 v206, v191, -v206, vcc
	v_cmp_ngt_f32_e32 vcc, s12, v204
	s_nop 1
	v_cndmask_b32_e32 v204, 1.0, v206, vcc
	v_sqrt_f32_e32 v204, v204
	s_nop 0
	v_mul_f32_e32 v203, v203, v204
	v_mul_f32_e32 v203, v203, v205
	ds_write2st64_b32 v116, v181, v203 offset0:104 offset1:170
	s_nop 0
	v_fmac_f32_e32 v203, v181, v180
	s_nop 0
	s_waitcnt lgkmcnt(5)
	v_add_f32_e32 v204, v73, v228
	v_mul_f32_e32 v204, 0xbfb8aa3b, v204
	v_exp_f32_e32 v204, v204
	v_add_f32_e32 v205, v98, v229
	ds_read2st64_b32 v[228:229], v119 offset0:104 offset1:170
	v_mul_f32_e32 v205, 0xbfb8aa3b, v205
	v_exp_f32_e32 v205, v205
	v_add_f32_e32 v204, 1.0, v204
	v_rcp_f32_e32 v204, v204
	v_add_f32_e32 v205, 1.0, v205
	v_rcp_f32_e32 v205, v205
	v_mul_f32_e32 v206, v106, v204
	s_nop 0
	s_nop 0
	s_waitcnt lgkmcnt(5)
	v_lshlrev_b32_e32 v207, 16, v232
	ds_read_u16 v232, v134 offset:2080
	v_mul_f32_e32 v204, 0x3fb8aa3b, v206
	v_add_f32_e32 v206, v206, v206
	v_mul_f32_e32 v208, 0x3fb8aa3b, v206
	v_rndne_f32_e32 v208, v208
	v_fmamk_f32 v209, v208, 0xbf317218, v206
	v_fmac_f32_e32 v209, 0x3102e308, v208
	v_fmamk_f32 v210, v209, 0x395133b1, v185
	v_cmp_eq_f32_e32 vcc, s35, v208
	v_cvt_i32_f32_e32 v208, v208
	v_fmaak_f32 v210, v209, v210, 0x3c0887f9
	v_fmaak_f32 v210, v209, v210, 0x3d2aaa81
	v_fmaak_f32 v210, v209, v210, 0x3e2aaaab
	v_fma_f32 v210, v209, v210, 0.5
	v_ldexp_f32 v208, 1.0, v208
	v_mul_f32_e32 v210, v209, v210
	v_cndmask_b32_e32 v208, v208, v198, vcc
	v_fmac_f32_e32 v209, v209, v210
	v_add_f32_e32 v210, -1.0, v208
	v_fmac_f32_e32 v210, v208, v209
	v_add_f32_e32 v208, v210, v210
	v_cndmask_b32_e32 v208, v210, v208, vcc
	v_cmp_nlt_f32_e32 vcc, s33, v206
	v_exp_f32_e32 v204, v204
	s_nop 0
	v_cndmask_b32_e64 v208, v191, -v208, vcc
	v_cmp_ngt_f32_e32 vcc, s12, v206
	s_nop 1
	v_cndmask_b32_e32 v206, 1.0, v208, vcc
	v_sqrt_f32_e32 v206, v206
	s_nop 0
	v_mul_f32_e32 v205, v205, v206
	v_mul_f32_e32 v205, v205, v207
	ds_write2st64_b32 v117, v204, v205 offset0:104 offset1:170
	s_nop 0
	v_fmac_f32_e32 v205, v204, v203
	s_nop 0
	s_waitcnt lgkmcnt(5)
	v_add_f32_e32 v206, v73, v236
	v_mul_f32_e32 v206, 0xbfb8aa3b, v206
	v_exp_f32_e32 v206, v206
	v_add_f32_e32 v207, v98, v237
	ds_read2st64_b32 v[236:237], v120 offset0:104 offset1:170
	v_mul_f32_e32 v207, 0xbfb8aa3b, v207
	v_exp_f32_e32 v207, v207
	v_add_f32_e32 v206, 1.0, v206
	v_rcp_f32_e32 v206, v206
	v_add_f32_e32 v207, 1.0, v207
	v_rcp_f32_e32 v207, v207
	v_mul_f32_e32 v208, v106, v206
	s_nop 0
	s_nop 0
	s_waitcnt lgkmcnt(5)
; DI float bf2f(u16 b) { return __uint_as_float(((unsigned)b) << 16); }
; DI float sigmoid_f(float x) { return __builtin_amdgcn_rcpf(1.f + __expf(-x)); }
; PH void lru_item(const Params& p, int layer, int b, int n, int dpart) {
;     ...
;     float P = 1.f, H = 0.f;
; #pragma unroll
;     for (int t = 0; t < 16; ++t) {
;       const int tok = sub * 16 + t;
;       const float rg = sigmoid_f(as_[tok * 33 + sch] + ba);
;       const float ig = sigmoid_f(bs_[tok * 33 + sch] + bx);
;       const float la = cl * rg;
;       const float xv = bf2f(xls[tok * 104 + dpart * 32 + sch]);
;       const float a = __expf(la);
;       const float bb = __builtin_amdgcn_sqrtf(-expm1f(2.f * la)) * ig * xv;
;       as_[tok * 33 + sch] = a;
;       bs_[tok * 33 + sch] = bb;
;       H = a * H + bb; P *= a;
;     }
	v_lshlrev_b32_e32 v209, 16, v224
	ds_read_u16 v224, v134 offset:2288
	v_mul_f32_e32 v206, 0x3fb8aa3b, v208
	v_add_f32_e32 v208, v208, v208
	v_mul_f32_e32 v210, 0x3fb8aa3b, v208
	v_rndne_f32_e32 v210, v210
	v_fmamk_f32 v211, v210, 0xbf317218, v208
	v_fmac_f32_e32 v211, 0x3102e308, v210
	v_fmamk_f32 v212, v211, 0x395133b1, v185
	v_cmp_eq_f32_e32 vcc, s35, v210
	v_cvt_i32_f32_e32 v210, v210
	v_fmaak_f32 v212, v211, v212, 0x3c0887f9
	v_fmaak_f32 v212, v211, v212, 0x3d2aaa81
	v_fmaak_f32 v212, v211, v212, 0x3e2aaaab
	v_fma_f32 v212, v211, v212, 0.5
	v_ldexp_f32 v210, 1.0, v210
	v_mul_f32_e32 v212, v211, v212
	v_cndmask_b32_e32 v210, v210, v198, vcc
	v_fmac_f32_e32 v211, v211, v212
	v_add_f32_e32 v212, -1.0, v210
	v_fmac_f32_e32 v212, v210, v211
	v_add_f32_e32 v210, v212, v212
	v_cndmask_b32_e32 v210, v212, v210, vcc
	v_cmp_nlt_f32_e32 vcc, s33, v208
	v_exp_f32_e32 v206, v206
	s_nop 0
	v_cndmask_b32_e64 v210, v191, -v210, vcc
	v_cmp_ngt_f32_e32 vcc, s12, v208
	s_nop 1
	v_cndmask_b32_e32 v208, 1.0, v210, vcc
	v_sqrt_f32_e32 v208, v208
	s_nop 0
	v_mul_f32_e32 v207, v207, v208
	v_mul_f32_e32 v207, v207, v209
	ds_write2st64_b32 v118, v206, v207 offset0:104 offset1:170
	s_nop 0
	v_fmac_f32_e32 v207, v206, v205
	s_nop 0
	s_waitcnt lgkmcnt(5)
	v_add_f32_e32 v208, v73, v228
	v_mul_f32_e32 v208, 0xbfb8aa3b, v208
	v_exp_f32_e32 v208, v208
	v_add_f32_e32 v209, v98, v229
	ds_read2st64_b32 v[228:229], v121 offset0:104 offset1:170
	v_mul_f32_e32 v209, 0xbfb8aa3b, v209
	v_exp_f32_e32 v209, v209
	v_add_f32_e32 v208, 1.0, v208
	v_rcp_f32_e32 v208, v208
	v_add_f32_e32 v209, 1.0, v209
	v_rcp_f32_e32 v209, v209
	v_mul_f32_e32 v210, v106, v208
	s_nop 0
	s_nop 0
	s_waitcnt lgkmcnt(5)
	v_lshlrev_b32_e32 v211, 16, v232
	ds_read_u16 v232, v134 offset:2496
	v_mul_f32_e32 v208, 0x3fb8aa3b, v210
	v_add_f32_e32 v210, v210, v210
	v_mul_f32_e32 v212, 0x3fb8aa3b, v210
	v_rndne_f32_e32 v212, v212
	v_fmamk_f32 v213, v212, 0xbf317218, v210
	v_fmac_f32_e32 v213, 0x3102e308, v212
	v_fmamk_f32 v214, v213, 0x395133b1, v185
	v_cmp_eq_f32_e32 vcc, s35, v212
	v_cvt_i32_f32_e32 v212, v212
	v_fmaak_f32 v214, v213, v214, 0x3c0887f9
	v_fmaak_f32 v214, v213, v214, 0x3d2aaa81
	v_fmaak_f32 v214, v213, v214, 0x3e2aaaab
	v_fma_f32 v214, v213, v214, 0.5
	v_ldexp_f32 v212, 1.0, v212
	v_mul_f32_e32 v214, v213, v214
	v_cndmask_b32_e32 v212, v212, v198, vcc
	v_fmac_f32_e32 v213, v213, v214
	v_add_f32_e32 v214, -1.0, v212
	v_fmac_f32_e32 v214, v212, v213
	v_add_f32_e32 v212, v214, v214
	v_cndmask_b32_e32 v212, v214, v212, vcc
	v_cmp_nlt_f32_e32 vcc, s33, v210
	v_exp_f32_e32 v208, v208
	s_nop 0
	v_cndmask_b32_e64 v212, v191, -v212, vcc
	v_cmp_ngt_f32_e32 vcc, s12, v210
	s_nop 1
	v_cndmask_b32_e32 v210, 1.0, v212, vcc
	v_sqrt_f32_e32 v210, v210
	s_nop 0
	v_mul_f32_e32 v209, v209, v210
	v_mul_f32_e32 v209, v209, v211
	ds_write2st64_b32 v119, v208, v209 offset0:104 offset1:170
	s_nop 0
	v_fmac_f32_e32 v209, v208, v207
	s_nop 0
	s_waitcnt lgkmcnt(5)
	v_add_f32_e32 v210, v73, v236
	v_mul_f32_e32 v210, 0xbfb8aa3b, v210
	v_exp_f32_e32 v210, v210
	v_add_f32_e32 v211, v98, v237
	ds_read2st64_b32 v[236:237], v122 offset0:104 offset1:170
	v_mul_f32_e32 v211, 0xbfb8aa3b, v211
	v_exp_f32_e32 v211, v211
	v_add_f32_e32 v210, 1.0, v210
	v_rcp_f32_e32 v210, v210
	v_add_f32_e32 v211, 1.0, v211
	v_rcp_f32_e32 v211, v211
	v_mul_f32_e32 v212, v106, v210
	s_nop 0
	s_nop 0
	s_waitcnt lgkmcnt(5)
	v_lshlrev_b32_e32 v213, 16, v224
	ds_read_u16 v224, v134 offset:2704
	v_mul_f32_e32 v210, 0x3fb8aa3b, v212
	v_add_f32_e32 v212, v212, v212
	v_mul_f32_e32 v214, 0x3fb8aa3b, v212
	v_rndne_f32_e32 v214, v214
	v_fmamk_f32 v215, v214, 0xbf317218, v212
	v_fmac_f32_e32 v215, 0x3102e308, v214
	v_fmamk_f32 v216, v215, 0x395133b1, v185
	v_cmp_eq_f32_e32 vcc, s35, v214
	v_cvt_i32_f32_e32 v214, v214
	v_fmaak_f32 v216, v215, v216, 0x3c0887f9
	v_fmaak_f32 v216, v215, v216, 0x3d2aaa81
	v_fmaak_f32 v216, v215, v216, 0x3e2aaaab
	v_fma_f32 v216, v215, v216, 0.5
	v_ldexp_f32 v214, 1.0, v214
	v_mul_f32_e32 v216, v215, v216
	v_cndmask_b32_e32 v214, v214, v198, vcc
	v_fmac_f32_e32 v215, v215, v216
	v_add_f32_e32 v216, -1.0, v214
	v_fmac_f32_e32 v216, v214, v215
	v_add_f32_e32 v214, v216, v216
	v_cndmask_b32_e32 v214, v216, v214, vcc
	v_cmp_nlt_f32_e32 vcc, s33, v212
	v_exp_f32_e32 v210, v210
	s_nop 0
	v_cndmask_b32_e64 v214, v191, -v214, vcc
	v_cmp_ngt_f32_e32 vcc, s12, v212
	s_nop 1
	v_cndmask_b32_e32 v212, 1.0, v214, vcc
	v_sqrt_f32_e32 v212, v212
	s_nop 0
	v_mul_f32_e32 v211, v211, v212
	v_mul_f32_e32 v211, v211, v213
	ds_write2st64_b32 v120, v210, v211 offset0:104 offset1:170
	s_nop 0
	v_fmac_f32_e32 v211, v210, v209
	s_nop 0
	s_waitcnt lgkmcnt(5)
	v_add_f32_e32 v212, v73, v228
	v_mul_f32_e32 v212, 0xbfb8aa3b, v212
	v_exp_f32_e32 v212, v212
	v_add_f32_e32 v213, v98, v229
	ds_read2st64_b32 v[228:229], v123 offset0:104 offset1:170
	v_mul_f32_e32 v213, 0xbfb8aa3b, v213
	v_exp_f32_e32 v213, v213
	v_add_f32_e32 v212, 1.0, v212
	v_rcp_f32_e32 v212, v212
	v_add_f32_e32 v213, 1.0, v213
	v_rcp_f32_e32 v213, v213
	v_mul_f32_e32 v214, v106, v212
	s_nop 0
	s_nop 0
	s_waitcnt lgkmcnt(5)
; DI float bf2f(u16 b) { return __uint_as_float(((unsigned)b) << 16); }
; DI float sigmoid_f(float x) { return __builtin_amdgcn_rcpf(1.f + __expf(-x)); }
; PH void lru_item(const Params& p, int layer, int b, int n, int dpart) {
;     ...
;     float P = 1.f, H = 0.f;
; #pragma unroll
;     for (int t = 0; t < 16; ++t) {
;       const int tok = sub * 16 + t;
;       const float rg = sigmoid_f(as_[tok * 33 + sch] + ba);
;       const float ig = sigmoid_f(bs_[tok * 33 + sch] + bx);
;       const float la = cl * rg;
;       const float xv = bf2f(xls[tok * 104 + dpart * 32 + sch]);
;       const float a = __expf(la);
;       const float bb = __builtin_amdgcn_sqrtf(-expm1f(2.f * la)) * ig * xv;
;       as_[tok * 33 + sch] = a;
;       bs_[tok * 33 + sch] = bb;
;       H = a * H + bb; P *= a;
;     }
;     if (b >= 0) {
;       Pc[sub * 32 + sch] = P; Hc[sub * 32 + sch] = H;
;       __syncthreads();
;       float carry = (c == 0) ? 0.f : hprev[(c & 1) * 32 + sch];
; #pragma unroll
;       for (int s = 0; s < 8; ++s) if (s < sub) carry = Pc[s * 32 + sch] * carry + Hc[s * 32 + sch];
	v_lshlrev_b32_e32 v215, 16, v232
	ds_read_u16 v232, v134 offset:2912
	v_mul_f32_e32 v212, 0x3fb8aa3b, v214
	v_add_f32_e32 v214, v214, v214
	v_mul_f32_e32 v216, 0x3fb8aa3b, v214
	v_rndne_f32_e32 v216, v216
	v_fmamk_f32 v217, v216, 0xbf317218, v214
	v_fmac_f32_e32 v217, 0x3102e308, v216
	v_fmamk_f32 v218, v217, 0x395133b1, v185
	v_cmp_eq_f32_e32 vcc, s35, v216
	v_cvt_i32_f32_e32 v216, v216
	v_fmaak_f32 v218, v217, v218, 0x3c0887f9
	v_fmaak_f32 v218, v217, v218, 0x3d2aaa81
	v_fmaak_f32 v218, v217, v218, 0x3e2aaaab
	v_fma_f32 v218, v217, v218, 0.5
	v_ldexp_f32 v216, 1.0, v216
	v_mul_f32_e32 v218, v217, v218
	v_cndmask_b32_e32 v216, v216, v198, vcc
	v_fmac_f32_e32 v217, v217, v218
	v_add_f32_e32 v218, -1.0, v216
	v_fmac_f32_e32 v218, v216, v217
	v_add_f32_e32 v216, v218, v218
	v_cndmask_b32_e32 v216, v218, v216, vcc
	v_cmp_nlt_f32_e32 vcc, s33, v214
	v_exp_f32_e32 v212, v212
	s_nop 0
	v_cndmask_b32_e64 v216, v191, -v216, vcc
	v_cmp_ngt_f32_e32 vcc, s12, v214
	s_nop 1
	v_cndmask_b32_e32 v214, 1.0, v216, vcc
	v_sqrt_f32_e32 v214, v214
	s_nop 0
	v_mul_f32_e32 v213, v213, v214
	v_mul_f32_e32 v213, v213, v215
	ds_write2st64_b32 v121, v212, v213 offset0:104 offset1:170
	s_nop 0
	v_fmac_f32_e32 v213, v212, v211
	s_nop 0
	s_waitcnt lgkmcnt(5)
	v_add_f32_e32 v214, v73, v236
	v_mul_f32_e32 v214, 0xbfb8aa3b, v214
	v_exp_f32_e32 v214, v214
	v_add_f32_e32 v215, v98, v237
	v_mul_f32_e32 v215, 0xbfb8aa3b, v215
	v_exp_f32_e32 v215, v215
	v_add_f32_e32 v214, 1.0, v214
	v_rcp_f32_e32 v214, v214
	v_add_f32_e32 v215, 1.0, v215
	v_rcp_f32_e32 v215, v215
	v_mul_f32_e32 v216, v106, v214
	s_nop 0
	s_nop 0
	s_waitcnt lgkmcnt(4)
	v_lshlrev_b32_e32 v217, 16, v224
	v_mul_f32_e32 v214, 0x3fb8aa3b, v216
	v_add_f32_e32 v216, v216, v216
	v_mul_f32_e32 v218, 0x3fb8aa3b, v216
	v_rndne_f32_e32 v218, v218
	v_fmamk_f32 v219, v218, 0xbf317218, v216
	v_fmac_f32_e32 v219, 0x3102e308, v218
	v_fmamk_f32 v220, v219, 0x395133b1, v185
	v_cmp_eq_f32_e32 vcc, s35, v218
	v_cvt_i32_f32_e32 v218, v218
	v_fmaak_f32 v220, v219, v220, 0x3c0887f9
	v_fmaak_f32 v220, v219, v220, 0x3d2aaa81
	v_fmaak_f32 v220, v219, v220, 0x3e2aaaab
	v_fma_f32 v220, v219, v220, 0.5
	v_ldexp_f32 v218, 1.0, v218
	v_mul_f32_e32 v220, v219, v220
	v_cndmask_b32_e32 v218, v218, v198, vcc
	v_fmac_f32_e32 v219, v219, v220
	v_add_f32_e32 v220, -1.0, v218
	v_fmac_f32_e32 v220, v218, v219
	v_add_f32_e32 v218, v220, v220
	v_cndmask_b32_e32 v218, v220, v218, vcc
	v_cmp_nlt_f32_e32 vcc, s33, v216
	v_exp_f32_e32 v214, v214
	s_nop 0
	v_cndmask_b32_e64 v218, v191, -v218, vcc
	v_cmp_ngt_f32_e32 vcc, s12, v216
	s_nop 1
	v_cndmask_b32_e32 v216, 1.0, v218, vcc
	v_sqrt_f32_e32 v216, v216
	s_nop 0
	v_mul_f32_e32 v215, v215, v216
	v_mul_f32_e32 v215, v215, v217
	ds_write2st64_b32 v122, v214, v215 offset0:104 offset1:170
	s_nop 0
	v_fmac_f32_e32 v215, v214, v213
	s_nop 0
	s_waitcnt lgkmcnt(3)
	v_add_f32_e32 v216, v73, v228
	v_mul_f32_e32 v216, 0xbfb8aa3b, v216
	v_exp_f32_e32 v216, v216
	s_nop 0
	v_add_f32_e32 v216, 1.0, v216
	v_rcp_f32_e32 v218, v216
	v_add_f32_e32 v216, v98, v229
	v_mul_f32_e32 v216, 0xbfb8aa3b, v216
	v_exp_f32_e32 v216, v216
	v_mul_f32_e32 v217, v106, v218
	s_nop 0
	v_add_f32_e32 v216, 1.0, v216
	v_rcp_f32_e32 v216, v216
	s_nop 0
	s_waitcnt lgkmcnt(2)
	v_lshlrev_b32_e32 v219, 16, v232
	v_mul_f32_e32 v218, 0x3fb8aa3b, v217
	v_add_f32_e32 v217, v217, v217
	v_mul_f32_e32 v220, 0x3fb8aa3b, v217
	v_rndne_f32_e32 v220, v220
	v_fmamk_f32 v221, v220, 0xbf317218, v217
	v_fmac_f32_e32 v221, 0x3102e308, v220
	v_fmamk_f32 v222, v221, 0x395133b1, v185
	v_cmp_eq_f32_e32 vcc, s35, v220
	v_cvt_i32_f32_e32 v220, v220
	v_fmaak_f32 v222, v221, v222, 0x3c0887f9
	v_fmaak_f32 v222, v221, v222, 0x3d2aaa81
	v_fmaak_f32 v222, v221, v222, 0x3e2aaaab
	v_fma_f32 v222, v221, v222, 0.5
	v_ldexp_f32 v220, 1.0, v220
	v_mul_f32_e32 v222, v221, v222
	v_cndmask_b32_e32 v220, v220, v198, vcc
	v_fmac_f32_e32 v221, v221, v222
	v_add_f32_e32 v222, -1.0, v220
	v_fmac_f32_e32 v222, v220, v221
	v_add_f32_e32 v220, v222, v222
	v_cndmask_b32_e32 v220, v222, v220, vcc
	v_cmp_nlt_f32_e32 vcc, s33, v217
	v_exp_f32_e32 v218, v218
	s_nop 0
	v_cndmask_b32_e64 v220, v191, -v220, vcc
	v_cmp_ngt_f32_e32 vcc, s12, v217
	s_nop 1
	v_cndmask_b32_e32 v217, 1.0, v220, vcc
	v_sqrt_f32_e32 v217, v217
	s_nop 0
	v_mul_f32_e32 v216, v216, v217
	v_mul_f32_e32 v217, v94, v167
	v_mul_f32_e32 v217, v217, v169
	v_mul_f32_e32 v217, v217, v171
	v_mul_f32_e32 v217, v217, v173
	v_mul_f32_e32 v217, v217, v175
	v_mul_f32_e32 v217, v217, v177
	v_mul_f32_e32 v217, v217, v179
	v_mul_f32_e32 v217, v217, v181
	v_mul_f32_e32 v217, v217, v204
	v_mul_f32_e32 v217, v217, v206
	v_mul_f32_e32 v217, v217, v208
	v_mul_f32_e32 v217, v217, v210
	v_mul_f32_e32 v217, v217, v212
	v_mul_f32_e32 v216, v216, v219
	v_mul_f32_e32 v217, v217, v214
	ds_write2st64_b32 v123, v218, v216 offset0:104 offset1:170
	v_mul_f32_e32 v217, v217, v218
	v_fmac_f32_e32 v216, v218, v215
	ds_write2st64_b32 v107, v217, v216 offset0:236 offset1:240
	s_nop 0
	s_waitcnt lgkmcnt(0)
	s_barrier
	s_cbranch_scc1 .LBB0_475
	v_and_b32_e32 v94, 32, v124
	v_lshl_add_u32 v94, v94, 2, v72
	ds_read_b32 v94, v94 offset:62464
	s_and_saveexec_b64 s[6:7], s[38:39]
	s_cbranch_execz .LBB0_456

; DI float bf2f(u16 b) { return __uint_as_float(((unsigned)b) << 16); }
; DI float silu_f(float x) { return x * __builtin_amdgcn_rcpf(1.f + __expf(-x)); }
; PH void lru_item(const Params& p, int layer, int b, int n, int dpart) {
;     ...
;       float hh = carry;
; #pragma unroll
;       for (int t = 0; t < 16; ++t) {
;         const int tok = sub * 16 + t;
;         const float a = as_[tok * 33 + sch], bb = bs_[tok * 33 + sch];
;         hh = a * hh + bb;
;         const size_t row = (size_t)(base + tok);
;         const float g = bf2f(gcur[t]);
;         MIX[row * 2048 + 512 + chg] = f2bf(hh * silu_f(g));
;       }
.LBB0_464:
	s_or_b64 exec, exec, s[6:7]
	ds_read2st64_b32 v[166:167], v86 offset0:104 offset1:170
	ds_read2st64_b32 v[224:225], v87 offset0:104 offset1:170
	ds_read2st64_b32 v[228:229], v89 offset0:104 offset1:170
	ds_read2st64_b32 v[232:233], v113 offset0:104 offset1:170
	ds_read2st64_b32 v[236:237], v114 offset0:104 offset1:170
	v_lshlrev_b32_e32 v165, 16, v165
	s_mov_b32 s6, 0x1b719000
	v_lshlrev_b32_e32 v164, 16, v164
	v_lshlrev_b32_e32 v163, 16, v163
	s_nop 0
	s_waitcnt lgkmcnt(4)
	v_fmac_f32_e32 v167, v94, v166
	v_lshlrev_b32_e32 v94, 16, v95
	v_mul_f32_e32 v95, 0xbfb8aa3b, v94
	v_exp_f32_e32 v95, v95
	v_lshlrev_b32_e32 v159, 16, v159
	v_lshlrev_b32_e32 v158, 16, v158
	v_lshlrev_b32_e32 v157, 16, v157
	v_add_f32_e32 v95, 1.0, v95
	v_rcp_f32_e32 v95, v95
	v_lshlrev_b32_e32 v156, 16, v156
	v_lshlrev_b32_e32 v154, 16, v154
	v_lshlrev_b32_e32 v148, 16, v148
	v_mul_f32_e32 v94, v95, v94
	v_mul_f32_e32 v94, v94, v167
	v_cvt_pk_bf16_f32 v166, v94, s0
	v_lshl_add_u64 v[94:95], v[92:93], 0, s[0:1]
	v_add_co_u32_e32 v168, vcc, 0x1b718000, v94
	v_lshlrev_b32_e32 v143, 16, v143
	s_nop 0
	v_addc_co_u32_e32 v169, vcc, 0, v95, vcc
	global_store_short v[168:169], v166, off offset:1024
	v_mul_f32_e32 v166, 0xbfb8aa3b, v165
	v_exp_f32_e32 v166, v166
	ds_read2st64_b32 v[168:169], v88 offset0:104 offset1:170
	v_lshlrev_b32_e32 v137, 16, v137
	v_lshlrev_b32_e32 v135, 16, v135
	v_add_f32_e32 v166, 1.0, v166
	v_rcp_f32_e32 v166, v166
	s_nop 0
	s_waitcnt lgkmcnt(0)
	v_fmac_f32_e32 v169, v167, v168
	v_lshlrev_b32_e32 v97, 16, v97
	v_lshlrev_b32_e32 v96, 16, v96
	v_mul_f32_e32 v165, v166, v165
	v_mul_f32_e32 v165, v165, v169
	v_add_co_u32_e32 v166, vcc, s6, v94
	v_cvt_pk_bf16_f32 v165, v165, s0
	s_nop 0
	v_addc_co_u32_e32 v167, vcc, 0, v95, vcc
	global_store_short v[166:167], v165, off offset:1024
	v_mul_f32_e32 v165, 0xbfb8aa3b, v164
	v_exp_f32_e32 v165, v165
	s_nop 0
	s_mov_b32 s6, 0x1b71a000
	v_add_f32_e32 v165, 1.0, v165
	v_rcp_f32_e32 v165, v165
	s_nop 0
	v_fmac_f32_e32 v225, v169, v224
	v_mul_f32_e32 v164, v165, v164
	v_mul_f32_e32 v164, v164, v225
	v_cvt_pk_bf16_f32 v166, v164, s0
	v_add_co_u32_e32 v164, vcc, s6, v94
	s_mov_b32 s6, 0x1b71b000
	s_nop 0
	v_addc_co_u32_e32 v165, vcc, 0, v95, vcc
	global_store_short v[164:165], v166, off offset:1024
	s_nop 0
	v_add_co_u32_e32 v166, vcc, s6, v94
	s_mov_b32 s6, 0x1b71c000
	s_nop 0
	v_fmac_f32_e32 v229, v225, v228
	ds_read2st64_b32 v[224:225], v116 offset0:104 offset1:170
	v_mul_f32_e32 v164, 0xbfb8aa3b, v163
	v_exp_f32_e32 v164, v164
	v_addc_co_u32_e32 v167, vcc, 0, v95, vcc
	v_add_f32_e32 v164, 1.0, v164
	v_rcp_f32_e32 v164, v164
	s_nop 0
	v_mul_f32_e32 v163, v164, v163
	v_mul_f32_e32 v163, v163, v229
	v_cvt_pk_bf16_f32 v163, v163, s0
	global_store_short v[166:167], v163, off offset:1024
	v_mul_f32_e32 v163, 0xbfb8aa3b, v159
	v_exp_f32_e32 v163, v163
	ds_read2st64_b32 v[166:167], v112 offset0:104 offset1:170
	v_add_co_u32_e32 v164, vcc, s6, v94
	v_add_f32_e32 v163, 1.0, v163
	v_rcp_f32_e32 v163, v163
	s_nop 0
	s_waitcnt lgkmcnt(0)
	v_fmac_f32_e32 v167, v229, v166
	ds_read2st64_b32 v[228:229], v117 offset0:104 offset1:170
	v_addc_co_u32_e32 v165, vcc, 0, v95, vcc
	v_mul_f32_e32 v159, v163, v159
	v_mul_f32_e32 v159, v159, v167
	v_cvt_pk_bf16_f32 v159, v159, s0
	global_store_short v[164:165], v159, off offset:1024
	v_mul_f32_e32 v159, 0xbfb8aa3b, v158
	v_exp_f32_e32 v159, v159
	s_nop 0
	s_mov_b32 s6, 0x1b71d000
	v_add_f32_e32 v159, 1.0, v159
	v_rcp_f32_e32 v159, v159
	s_nop 0
	v_fmac_f32_e32 v233, v167, v232
	v_mul_f32_e32 v158, v159, v158
	v_mul_f32_e32 v158, v158, v233
	v_cvt_pk_bf16_f32 v163, v158, s0
	v_add_co_u32_e32 v158, vcc, s6, v94
	s_mov_b32 s6, 0x1b71e000
	s_nop 0
	v_addc_co_u32_e32 v159, vcc, 0, v95, vcc
	global_store_short v[158:159], v163, off offset:1024
	s_nop 0
	v_add_co_u32_e32 v164, vcc, s6, v94
	s_mov_b32 s6, 0x1b71f000
	s_nop 0
	v_fmac_f32_e32 v237, v233, v236
	ds_read2st64_b32 v[232:233], v118 offset0:104 offset1:170
	v_mul_f32_e32 v158, 0xbfb8aa3b, v157
	v_exp_f32_e32 v158, v158
	v_addc_co_u32_e32 v165, vcc, 0, v95, vcc
	v_add_f32_e32 v158, 1.0, v158
	v_rcp_f32_e32 v158, v158
	s_nop 0
	v_mul_f32_e32 v157, v158, v157
	v_mul_f32_e32 v157, v157, v237
	v_cvt_pk_bf16_f32 v157, v157, s0
	global_store_short v[164:165], v157, off offset:1024
	v_mul_f32_e32 v157, 0xbfb8aa3b, v156
	v_exp_f32_e32 v157, v157
	ds_read2st64_b32 v[164:165], v115 offset0:104 offset1:170
	v_add_f32_e32 v157, 1.0, v157
	v_rcp_f32_e32 v157, v157
	s_nop 0
	s_waitcnt lgkmcnt(0)
; DI float bf2f(u16 b) { return __uint_as_float(((unsigned)b) << 16); }
; DI float silu_f(float x) { return x * __builtin_amdgcn_rcpf(1.f + __expf(-x)); }
; PH void lru_item(const Params& p, int layer, int b, int n, int dpart) {
;     ...
;       float hh = carry;
; #pragma unroll
;       for (int t = 0; t < 16; ++t) {
;         const int tok = sub * 16 + t;
;         const float a = as_[tok * 33 + sch], bb = bs_[tok * 33 + sch];
;         hh = a * hh + bb;
;         const size_t row = (size_t)(base + tok);
;         const float g = bf2f(gcur[t]);
;         MIX[row * 2048 + 512 + chg] = f2bf(hh * silu_f(g));
;       }
;       if (sub == 7) {
;         hprev[((c + 1) & 1) * 32 + sch] = hh;
;         if (c == 15) p.out[O_PLH + (size_t)(layer * 8 + b) * 768 + chg] = hh;
;       }
	v_fmac_f32_e32 v165, v237, v164
	ds_read2st64_b32 v[236:237], v119 offset0:104 offset1:170
	v_mul_f32_e32 v156, v157, v156
	v_mul_f32_e32 v156, v156, v165
	v_cvt_pk_bf16_f32 v158, v156, s0
	v_add_co_u32_e32 v156, vcc, s6, v94
	s_mov_b32 s6, 0x1b720000
	s_nop 0
	v_addc_co_u32_e32 v157, vcc, 0, v95, vcc
	global_store_short v[156:157], v158, off offset:1024
	s_nop 0
	v_add_co_u32_e32 v158, vcc, s6, v94
	s_mov_b32 s6, 0x1b721000
	s_nop 0
	v_addc_co_u32_e32 v159, vcc, 0, v95, vcc
	s_nop 0
	v_fmac_f32_e32 v225, v165, v224
	v_mul_f32_e32 v156, 0xbfb8aa3b, v154
	v_exp_f32_e32 v156, v156
	s_nop 0
	v_add_f32_e32 v156, 1.0, v156
	v_rcp_f32_e32 v156, v156
	s_nop 0
	v_mul_f32_e32 v154, v156, v154
	v_mul_f32_e32 v154, v154, v225
	v_cvt_pk_bf16_f32 v154, v154, s0
	global_store_short v[158:159], v154, off offset:1024
	v_mul_f32_e32 v154, 0xbfb8aa3b, v148
	v_exp_f32_e32 v154, v154
	s_nop 0
	v_add_co_u32_e32 v156, vcc, s6, v94
	v_add_f32_e32 v154, 1.0, v154
	v_rcp_f32_e32 v154, v154
	s_nop 0
	v_fmac_f32_e32 v229, v225, v228
	ds_read2st64_b32 v[224:225], v120 offset0:104 offset1:170
	v_addc_co_u32_e32 v157, vcc, 0, v95, vcc
	v_mul_f32_e32 v148, v154, v148
	v_mul_f32_e32 v148, v148, v229
	v_cvt_pk_bf16_f32 v148, v148, s0
	global_store_short v[156:157], v148, off offset:1024
	v_mul_f32_e32 v148, 0xbfb8aa3b, v143
	v_exp_f32_e32 v148, v148
	s_nop 0
	s_mov_b32 s6, 0x1b722000
	v_add_co_u32_e32 v158, vcc, s6, v94
	v_add_f32_e32 v148, 1.0, v148
	v_rcp_f32_e32 v148, v148
	s_nop 0
	v_fmac_f32_e32 v233, v229, v232
	v_addc_co_u32_e32 v159, vcc, 0, v95, vcc
	v_mul_f32_e32 v143, v148, v143
	v_mul_f32_e32 v143, v143, v233
	v_cvt_pk_bf16_f32 v143, v143, s0
	global_store_short v[158:159], v143, off offset:1024
	v_mul_f32_e32 v143, 0xbfb8aa3b, v137
	v_exp_f32_e32 v143, v143
	s_nop 0
	s_mov_b32 s6, 0x1b723000
	v_add_co_u32_e32 v156, vcc, s6, v94
	v_add_f32_e32 v143, 1.0, v143
	v_rcp_f32_e32 v143, v143
	s_nop 0
	s_waitcnt lgkmcnt(1)
	v_fmac_f32_e32 v237, v233, v236
	v_addc_co_u32_e32 v157, vcc, 0, v95, vcc
	v_mul_f32_e32 v137, v143, v137
	v_mul_f32_e32 v137, v137, v237
	v_cvt_pk_bf16_f32 v137, v137, s0
	global_store_short v[156:157], v137, off offset:1024
	v_mul_f32_e32 v137, 0xbfb8aa3b, v135
	v_exp_f32_e32 v137, v137
	s_nop 0
	s_mov_b32 s6, 0x1b724000
	v_add_co_u32_e32 v158, vcc, s6, v94
	v_add_f32_e32 v137, 1.0, v137
	v_rcp_f32_e32 v137, v137
	s_nop 0
	s_waitcnt lgkmcnt(0)
	v_fmac_f32_e32 v225, v237, v224
	v_addc_co_u32_e32 v159, vcc, 0, v95, vcc
	v_mul_f32_e32 v135, v137, v135
	v_mul_f32_e32 v135, v135, v225
	v_cvt_pk_bf16_f32 v135, v135, s0
	global_store_short v[158:159], v135, off offset:1024
	v_mul_f32_e32 v135, 0xbfb8aa3b, v97
	v_exp_f32_e32 v135, v135
	ds_read2st64_b32 v[158:159], v121 offset0:104 offset1:170
	s_mov_b32 s6, 0x1b725000
	v_add_co_u32_e32 v156, vcc, s6, v94
	v_add_f32_e32 v135, 1.0, v135
	v_rcp_f32_e32 v135, v135
	s_nop 0
	s_waitcnt lgkmcnt(0)
	v_fmac_f32_e32 v159, v225, v158
	v_addc_co_u32_e32 v157, vcc, 0, v95, vcc
	v_mul_f32_e32 v97, v135, v97
	v_mul_f32_e32 v97, v97, v159
	v_cvt_pk_bf16_f32 v97, v97, s0
	global_store_short v[156:157], v97, off offset:1024
	v_mul_f32_e32 v97, 0xbfb8aa3b, v96
	v_exp_f32_e32 v97, v97
	ds_read2st64_b32 v[156:157], v122 offset0:104 offset1:170
	s_mov_b32 s6, 0x1b726000
	v_add_f32_e32 v97, 1.0, v97
	v_rcp_f32_e32 v97, v97
	s_nop 0
	s_waitcnt lgkmcnt(0)
	v_fmac_f32_e32 v157, v159, v156
	v_mul_f32_e32 v96, v97, v96
	v_mul_f32_e32 v96, v96, v157
	v_cvt_pk_bf16_f32 v135, v96, s0
	v_add_co_u32_e32 v96, vcc, s6, v94
	s_nop 1
	v_addc_co_u32_e32 v97, vcc, 0, v95, vcc
	global_store_short v[96:97], v135, off offset:1024
	ds_read2st64_b32 v[96:97], v123 offset0:104 offset1:170
	v_add_co_u32_e32 v94, vcc, 0x1b727000, v94
	s_nop 0
	s_waitcnt lgkmcnt(0)
	v_fmac_f32_e32 v97, v157, v96
	s_waitcnt vmcnt(37)
	v_lshlrev_b32_e32 v96, 16, v125
	v_mul_f32_e32 v125, 0xbfb8aa3b, v96
	v_exp_f32_e32 v125, v125
	v_addc_co_u32_e32 v95, vcc, 0, v95, vcc
	v_add_f32_e32 v125, 1.0, v125
	v_rcp_f32_e32 v125, v125
	s_nop 0
	v_mul_f32_e32 v96, v125, v96
	v_mul_f32_e32 v96, v96, v97
	v_cvt_pk_bf16_f32 v96, v96, s0
	global_store_short v[94:95], v96, off offset:1024
	s_and_saveexec_b64 s[6:7], s[36:37]
	s_xor_b64 s[6:7], exec, s[6:7]
	v_add_u32_e32 v124, 32, v124
	s_andn2_saveexec_b64 s[6:7], s[6:7]
	s_cbranch_execz .LBB0_452
	v_add_u32_e32 v124, 32, v124
	v_and_b32_e32 v94, 32, v124
	v_lshl_add_u32 v94, v94, 2, v72
	s_cmp_lg_u32 s0, 0x780000
	ds_write_b32 v94, v97 offset:62464
	s_cbranch_scc1 .LBB0_452
	global_store_dword v[90:91], v97, off
	s_branch .LBB0_452

; __global__ void __launch_bounds__(256, 2) mega(Params p) {
;     ...
;     for (int rep = 0; rep < REP_2B; ++rep) {
;       bool first = true;
;       for (;;) {
;         int it;
;         if (first) { it = (int)blockIdx.x; first = false; }
;         else it = next_item(ctr + layer * 2 + 1 + 8 * rep, &slot) + (int)gridDim.x;
;         if (rep > 0) { it += PROBE_2B_LO; if (it >= PROBE_2B_HI) break; }
;         if (it >= 288 + 192 + 24 + 256 + 1536) break;
;         it = (it < 192) ? (it + 384) : ((it < 480) ? (it - 192) : ((it < 504) ? (it + 608) : ((it < 760) ? (it + 328) : (it + 352))));
;         if (it < 384) { const int v = it % 96; ssd_prompt_item<0>(p, layer, v / 12, v % 12, it / 96); }
;         else if (it < 576) { const int v = it - 384; lru_item(p, layer, v / 24, (v % 24) / 3, v % 3); }
;         else if (it < 832) attn_prompt_item(p, layer, it - 576);
;         else if (it < 1088) attn_decode_item(p, layer, it - 832);
;         else if (it < 1112) { const int v = it - 1088; lru_item(p, layer, -1, v / 3, v % 3); }
;         else { const int v = it - 1112; ssd_decode_item(p, layer, v / 12, v % 12); }
;       }
;       xcd_barrier(xb);
.LBB0_476:
	s_nop 0
	s_nop 0
	s_nop 0
	s_nop 0
	s_nop 0
	s_nop 0
	s_nop 0
	s_nop 0
	s_nop 0
	s_nop 0
	s_nop 0
	s_nop 0
	s_nop 0
	s_nop 0
	s_nop 0
	s_nop 0
	s_nop 0
	s_nop 0
	s_nop 0
	s_nop 0
	s_nop 0
	s_nop 0
	s_nop 0
	s_nop 0
	s_nop 0
	s_nop 0
	s_nop 0
	s_nop 0
	s_nop 0
	s_nop 0
	s_nop 0
	s_nop 0
	s_nop 0
	s_nop 0
	s_nop 0
	s_nop 0
	s_nop 0
	s_nop 0
	s_nop 0
	s_nop 0
	s_nop 0
	s_nop 0
	s_nop 0
	s_nop 0
	s_nop 0
	s_nop 0
	s_nop 0
	s_nop 0
	s_cbranch_execnz .LBB0_609
